# scan consumer y-store addressing simplified (4 instr/store); first phase seam uses the XCD barrier instead of cg grid sync
# speedup vs baseline: 1.0393x; 1.0000x over previous
; __device__ __forceinline__ bf16_t f2bf(float f) { return (bf16_t)(pkbf(f, 0.f) & 0xffffu); }
; #define SC2_CHUNK(C, base, Tn, cc, wy) int base, Tn, cc; bool wy; if ((C) < 16) { base = ML + b * 256; Tn = 256; cc = (C); wy = ctx_out; } else { base = b * 2048; Tn = 2048; cc = (C) - 16; wy = true; }
; __device__ __forceinline__ void scan_unit_mfma(const TI ti, CArgs& a, int l, int u, bool ctx_out, unsigned char* ldsg) {
;     ...
;                 {
;                     SC2_CHUNK(C, base_, Tn_, cc_, wy_);
;                     if (wy_) {
; #pragma unroll
;                         for (int q = 8; q < 16; ++q) {
;                             const int t = (q & 3) + 8 * ((q >> 2) - 2) + 4 * h; const int tok = SC2_TOK(Tn_, cc_, t);
;                             Y[(size_t)(base_ + tok) * 1024 + hh * 64 + 32 * it + r] = f2bf(Z[q]);
;                         }
;                     }
;                 }
.LBB0_327:
	v_lshl_or_b32 v4, s3, 4, v87
	v_sub_u32_e32 v2, s18, v4
	v_cndmask_b32_e64 v4, v2, v4, s[60:61]
	v_add_u32_e32 v4, s1, v4
	v_cndmask_b32_e64 v110, -1, 1, s[60:61]
	s_movk_i32 s4, 0x800
	v_mad_u64_u32 v[2:3], vcc, v4, s4, v[82:83]
	v_cvt_pk_bf16_f32 v5, v72, s0
	global_store_short v[2:3], v5, off
	v_mad_i32_i24 v111, v110, 1, v4
	v_mad_u64_u32 v[2:3], vcc, v111, s4, v[82:83]
	v_cvt_pk_bf16_f32 v5, v73, s0
	global_store_short v[2:3], v5, off
	v_mad_i32_i24 v111, v110, 2, v4
	v_mad_u64_u32 v[2:3], vcc, v111, s4, v[82:83]
	v_cvt_pk_bf16_f32 v5, v74, s0
	global_store_short v[2:3], v5, off
	v_mad_i32_i24 v111, v110, 3, v4
	v_mad_u64_u32 v[2:3], vcc, v111, s4, v[82:83]
	v_cvt_pk_bf16_f32 v5, v75, s0
	global_store_short v[2:3], v5, off
	v_mad_i32_i24 v111, v110, 8, v4
	v_mad_u64_u32 v[2:3], vcc, v111, s4, v[82:83]
	v_cvt_pk_bf16_f32 v5, v76, s0
	global_store_short v[2:3], v5, off
	v_mad_i32_i24 v111, v110, 9, v4
	v_mad_u64_u32 v[2:3], vcc, v111, s4, v[82:83]
	v_cvt_pk_bf16_f32 v5, v77, s0
	global_store_short v[2:3], v5, off
	v_mad_i32_i24 v111, v110, 10, v4
	v_mad_u64_u32 v[2:3], vcc, v111, s4, v[82:83]
	v_cvt_pk_bf16_f32 v5, v78, s0
	global_store_short v[2:3], v5, off
	v_mad_i32_i24 v111, v110, 11, v4
	v_mad_u64_u32 v[2:3], vcc, v111, s4, v[82:83]
	v_cvt_pk_bf16_f32 v5, v79, s0
	global_store_short v[2:3], v5, off
	s_branch .LBB0_321

; __device__ __forceinline__ void xcd_barrier(const XcdBarrier& b) {
;     asm volatile("s_waitcnt vmcnt(0)" ::: "memory");
;     __syncthreads();
;     if (threadIdx.x == 0) {
;         unsigned* bar = b.bar;
;         __builtin_amdgcn_s_waitcnt(0);
;         unsigned nloc = b.st[0], nx = b.st[1];
;         if (nloc == 0u) { xcd_barrier_complete(bar, b.x, nloc, nx); b.st[0] = nloc; b.st[1] = nx; }
; __global__ void __launch_bounds__(512, 2) mega_fwd(Args a_) {
;     ...
;         if (ph + 1 < ph_hi) { if (ph == ph_lo) grid.sync(); else xcd_barrier(xbar); }
.LBB0_944:
	s_cmp_lg_u32 s2, s58
	s_waitcnt vmcnt(0)
	s_waitcnt vmcnt(0) lgkmcnt(0)
	s_barrier
	s_mov_b64 s[0:1], exec
	v_readlane_b32 s2, v254, 6
	v_readlane_b32 s3, v254, 7
	s_and_b64 s[2:3], s[0:1], s[2:3]
	s_mov_b64 exec, s[2:3]
	s_cbranch_execz .LBB0_997
	v_readlane_b32 s2, v254, 62
	s_waitcnt vmcnt(0) expcnt(0) lgkmcnt(0)
	s_nop 0
	v_mov_b32_e32 v0, s2
	ds_read_b32 v3, v0
	v_readlane_b32 s2, v254, 63
	s_waitcnt lgkmcnt(0)
	v_cmp_ne_u32_e32 vcc, 0, v3
	v_mov_b32_e32 v0, s2
	ds_read_b32 v2, v0
	s_cbranch_vccnz .LBB0_961
	s_mov_b32 s11, 1
	s_branch .LBB0_949
